# attention phases: static issue priority (s_setprio 1) for waves 4-7, reset at phase end
# speedup vs baseline: 1.0073x; 1.0073x over previous
; #define PHASE(id) if constexpr (SEL < 0 || SEL == (id))
; template<int MODE,int THRL> __device__ __forceinline__ void attn_unit(int qb,const bf16*Q,const bf16*__restrict__ K,const bf16*__restrict__ V,bf16*O,const float*__restrict__ cum,const float*__restrict__ relb,const float thr,char*shm,const int wv){
;   const int tid=::mk_tid(wv); const int lane=tid&63,r32=lane&31,hi=lane>>5; const int wid=wv;
;   const int q0=qb*QB;
;   const bf16*Qw=Q+(long)(q0+wid*QBLK)*PITCH;
;   typedef __attribute__((address_space(3))) float* lds_fptr;
;   const lds_fptr kb3=(lds_fptr)(__attribute__((address_space(3))) char*)shm+LDS_KB/4;
;   if constexpr(MODE==0){ const float cref=cum[q0]; for(int i=tid;i<q0+QB;i+=NW*64)kb3[i]=(cref-cum[i])*1.4426950408889634f; }
;   int tskip=0;
;   if constexpr(MODE==0){
;     asm volatile("s_waitcnt lgkmcnt(0)\n\ts_barrier":::"memory");
;     const int ntf=(q0+QB)/KVBLK; const int c=(tid<ntf)?(kb3[64*tid+63]<=-thr?1:0):0;
;     const int cnt=__popcll(__ballot(c));
;     const __attribute__((address_space(3))) int* cw=(const __attribute__((address_space(3))) int*)((__attribute__((address_space(3))) char*)shm+LDS_CNT);
;     if(lane==0)((__attribute__((address_space(3))) int*)cw)[wid]=cnt;
;     asm volatile("s_waitcnt lgkmcnt(0)\n\ts_barrier":::"memory");
;     tskip=(cw[0]+cw[1]+cw[2]+cw[3])&~1; tskip=__builtin_amdgcn_readfirstlane(tskip);
;   }
; template <int l, int SEL> __device__ __forceinline__ void layer_body(const Args& args, LAS unsigned char* ldsp, unsigned char* lds, const int G, const int bx, const int vcu, const int wv) {
;     ...
;         PHASE(B + 1) {
;             typedef attn_body::bf16 abf;
;             const abf* pj = (const abf*)q_proj;
;     ...
;             for (int p = vcu; p < 256; p += G) { const int vh = p >> 5, s = p & 31;
;                 const unsigned* nr = q_ctl + 16; const float qn = sqrtf(__uint_as_float(nr[2 * vh]) + __uint_as_float(nr[2 * vh + 1])), kn = sqrtf(__uint_as_float(nr[16 + 2 * vh]) + __uint_as_float(nr[16 + 2 * vh + 1]));
;                 const float thr = 2.04f * qn * kn + 40.f;
;                 for (int half = 0; half < 2; ++half) { const int qb = half ? 63 - s : s;
;                     attn_body::attn_unit<0, 8>(qb, pj + (size_t)vh * M * 64, pj + (size_t)(8 + vh) * M * 64, pj + (size_t)(16 + vh) * M * 64, (abf*)q_yatt + vh * 64, q_cum + (size_t)vh * M, nullptr, thr, (char*)lds, wv); } }
.LBB0_362:
	s_or_b64 exec, exec, s[4:5]
	s_cmpk_lt_i32 s76, 0x100
	s_cselect_b64 s[6:7], -1, 0
	v_writelane_b32 v255, s6, 2
	s_mov_b64 s[4:5], s[0:1]
	s_cmpk_gt_i32 s76, 0xff
	v_writelane_b32 v255, s7, 3
	s_waitcnt lgkmcnt(0)
	s_barrier
	s_cbranch_scc1 .LBB0_544
	s_cmp_lt_u32 s68, 4
	s_cbranch_scc1 .Lprio_l0
	s_setprio 1
.Lprio_l0:
	s_load_dwordx2 s[10:11], s[4:5], 0xc0
	v_writelane_b32 v255, s36, 4
	s_movk_i32 s44, 0xe000
	s_mov_b32 s8, s94
	v_writelane_b32 v255, s37, 5
	s_waitcnt lgkmcnt(0)
	s_add_u32 s3, s10, 0x14500000
	s_addc_u32 s31, s11, 0
	s_lshl_b32 s4, s68, 2
	s_lshl_b32 s5, s68, 3
	s_add_i32 s15, s4, 0
	s_lshl_b32 s66, s68, 4
	s_lshl_b32 s35, s68, 5
	s_add_i32 s15, s15, 0x24800
	s_and_b32 s67, s66, 48
	s_and_b32 s75, s5, 0x1fffffe0
	s_cmp_lg_u32 0, -1
	s_cselect_b32 s4, 0, 0
	s_add_i32 s77, s74, s4
	s_lshl_b32 s4, s69, 2
	s_add_i32 s81, s77, 0x6000
	s_add_i32 s82, s4, 0
	s_lshl_b32 s4, s68, 12
	s_mov_b64 s[36:37], s[38:39]
	s_mov_b64 s[38:39], s[96:97]
	s_mov_b32 s13, 0
	s_add_i32 s83, s4, 0
	v_mov_b32_e32 v1, 0
	s_mov_b32 s84, 0xf800000
	v_mov_b32_e32 v197, 0x260
	s_movk_i32 s85, 0x1ff
	s_add_i32 s86, 0, 0x15000
	s_mov_b32 s14, 0x3fb8aa3b
	s_add_i32 s87, 0, 0x14800
	s_mov_b64 s[16:17], 0x800
	s_lshl_b32 s18, s5, 1
	s_lshl_b32 s20, s75, 1
	v_mov_b32_e32 v202, s77
	v_mov_b32_e32 v203, s81
	s_mov_b64 s[22:23], 0x2000
	v_mov_b32_e32 v204, s74
	s_mov_b64 s[24:25], 0x4000
	s_mov_b64 s[26:27], 0x6000
	s_mov_b64 s[28:29], 0xa000
	s_mov_b32 s45, -1
	s_mov_b32 s88, 0x41000000
	s_mov_b64 s[46:47], 0x1e500000
	v_mov_b32_e32 v205, 0xff800000
	s_mov_b32 s89, s76
	s_branch .LBB0_365

; __device__ __forceinline__ int mk_tid(int wv) { return (wv << 6) | lane_now(); }
; __device__ __forceinline__ unsigned xb_ld(unsigned* p)              { return __hip_atomic_load(p, __ATOMIC_RELAXED, __HIP_MEMORY_SCOPE_AGENT); }
; __device__ __forceinline__ void xcd_barrier_complete(unsigned* bar, unsigned x, unsigned& nloc, unsigned& nx) {
;     const unsigned G = gridDim.x * gridDim.y * gridDim.z;
;     unsigned sum, cnt, mine, sp = 0u;
;     for (;;) {
;         sum = 0u; cnt = 0u; mine = 0u;
; #pragma unroll
;         for (unsigned j = 0; j < 16; ++j) { const unsigned c = xb_ld(&bar[XB_XCNT(j)]); sum += c; cnt += (c > 0u) ? 1u : 0u; mine = (j == x) ? c : mine; }
;         if (sum == G) break;
; __device__ __forceinline__ void xcd_barrier(const XcdBarrier& b, const int wv) {
;     asm volatile("s_waitcnt vmcnt(0)" ::: "memory");
;     __syncthreads();
;     if (mk_tid(wv) == 0) {
;         unsigned* bar = b.bar;
;         __builtin_amdgcn_s_waitcnt(0);
;         unsigned nloc = b.st[0], nx = b.st[1];
;         if (nloc == 0u) { xcd_barrier_complete(bar, b.x, nloc, nx); b.st[0] = nloc; b.st[1] = nx; }
.LBB0_544:
	s_setprio 0
	s_mov_b64 s[6:7], s[0:1]
	s_getreg_b32 s3, hwreg(HW_REG_XCC_ID, 0, 4)
	s_waitcnt vmcnt(0)
	s_barrier
	v_mbcnt_lo_u32_b32 v0, -1, 0
	v_mbcnt_hi_u32_b32 v0, -1, v0
	s_nop 0
	v_or_b32_e32 v0, s69, v0
	v_cmp_eq_u32_e32 vcc, 0, v0
	s_and_saveexec_b64 s[4:5], vcc
	s_cbranch_execz .LBB0_596
	s_add_i32 s10, 0, 0x24840
	v_mov_b32_e32 v0, s10
	s_load_dwordx2 s[6:7], s[6:7], 0xc0
	s_waitcnt vmcnt(0) expcnt(0) lgkmcnt(0)
	ds_read_b32 v2, v0
	s_add_i32 s10, 0, 0x24844
	v_mov_b32_e32 v0, s10
	ds_read_b32 v0, v0
	s_and_b32 s3, s3, 15
	s_waitcnt lgkmcnt(1)
	v_cmp_ne_u32_e32 vcc, 0, v2
	s_cbranch_vccnz .LBB0_560
	s_add_u32 s10, s6, 0x4200
	s_addc_u32 s11, s7, 0
	s_add_u32 s12, s6, 0x4400
	s_addc_u32 s13, s7, 0
	s_add_u32 s14, s6, 0x4500
	s_addc_u32 s15, s7, 0
	s_add_u32 s16, s6, 0x4600
	s_addc_u32 s17, s7, 0
	s_add_u32 s18, s6, 0x4700
	s_addc_u32 s19, s7, 0
	s_add_u32 s20, s6, 0x4800
	s_addc_u32 s21, s7, 0
	s_add_u32 s22, s6, 0x4900
	s_addc_u32 s23, s7, 0
	s_add_u32 s24, s6, 0x4a00
	s_addc_u32 s25, s7, 0
	s_add_u32 s26, s6, 0x4b00
	s_addc_u32 s27, s7, 0
	s_add_u32 s28, s6, 0x4c00
	s_addc_u32 s29, s7, 0
	s_add_u32 s44, s6, 0x4d00
	s_addc_u32 s45, s7, 0
	s_add_u32 s46, s6, 0x4e00
	s_addc_u32 s47, s7, 0
	s_add_u32 s48, s6, 0x4f00
	s_addc_u32 s49, s7, 0
	s_add_u32 s50, s6, 0x5000
	s_addc_u32 s51, s7, 0
	s_add_u32 s52, s6, 0x5100
	s_addc_u32 s53, s7, 0
	s_add_u32 s54, s6, 0x5200
	s_addc_u32 s55, s7, 0
	s_mul_i32 s31, s37, s33
	s_add_u32 s56, s6, 0x5300
	s_mul_i32 s31, s31, s36
	s_addc_u32 s57, s7, 0
	s_mov_b32 s35, 1
	v_mov_b32_e32 v16, 0
	s_branch .LBB0_548

; #define PHASE(id) if constexpr (SEL < 0 || SEL == (id))
; template<int MODE,int THRL> __device__ __forceinline__ void attn_unit(int qb,const bf16*Q,const bf16*__restrict__ K,const bf16*__restrict__ V,bf16*O,const float*__restrict__ cum,const float*__restrict__ relb,const float thr,char*shm,const int wv){
;   const int tid=::mk_tid(wv); const int lane=tid&63,r32=lane&31,hi=lane>>5; const int wid=wv;
;   const int q0=qb*QB;
;   const bf16*Qw=Q+(long)(q0+wid*QBLK)*PITCH;
;   typedef __attribute__((address_space(3))) float* lds_fptr;
;   const lds_fptr kb3=(lds_fptr)(__attribute__((address_space(3))) char*)shm+LDS_KB/4;
;   if constexpr(MODE==0){ const float cref=cum[q0]; for(int i=tid;i<q0+QB;i+=NW*64)kb3[i]=(cref-cum[i])*1.4426950408889634f; }
;   int tskip=0;
;   if constexpr(MODE==0){
;     asm volatile("s_waitcnt lgkmcnt(0)\n\ts_barrier":::"memory");
;     const int ntf=(q0+QB)/KVBLK; const int c=(tid<ntf)?(kb3[64*tid+63]<=-thr?1:0):0;
;     const int cnt=__popcll(__ballot(c));
;     const __attribute__((address_space(3))) int* cw=(const __attribute__((address_space(3))) int*)((__attribute__((address_space(3))) char*)shm+LDS_CNT);
;     if(lane==0)((__attribute__((address_space(3))) int*)cw)[wid]=cnt;
;     asm volatile("s_waitcnt lgkmcnt(0)\n\ts_barrier":::"memory");
;     tskip=(cw[0]+cw[1]+cw[2]+cw[3])&~1; tskip=__builtin_amdgcn_readfirstlane(tskip);
;   }
; template <int l, int SEL> __device__ __forceinline__ void layer_body(const Args& args, LAS unsigned char* ldsp, unsigned char* lds, const int G, const int bx, const int vcu, const int wv) {
;     ...
;         PHASE(B + 1) {
;             typedef attn_body::bf16 abf;
;             const abf* pj = (const abf*)q_proj;
;     ...
;             for (int p = vcu; p < 256; p += G) { const int vh = p >> 5, s = p & 31;
;                 const unsigned* nr = q_ctl + 16; const float qn = sqrtf(__uint_as_float(nr[2 * vh]) + __uint_as_float(nr[2 * vh + 1])), kn = sqrtf(__uint_as_float(nr[16 + 2 * vh]) + __uint_as_float(nr[16 + 2 * vh + 1]));
;                 const float thr = 2.04f * qn * kn + 40.f;
;                 for (int half = 0; half < 2; ++half) { const int qb = half ? 63 - s : s;
;                     attn_body::attn_unit<0, 8>(qb, pj + (size_t)vh * M * 64, pj + (size_t)(8 + vh) * M * 64, pj + (size_t)(16 + vh) * M * 64, (abf*)q_yatt + vh * 64, q_cum + (size_t)vh * M, nullptr, thr, (char*)lds, wv); } }
.LBB0_1402:
	s_or_b64 exec, exec, s[8:9]
	v_readlane_b32 s10, v255, 2
	v_readlane_b32 s11, v255, 3
	s_mov_b64 s[8:9], s[0:1]
	s_andn2_b64 vcc, exec, s[10:11]
	s_waitcnt lgkmcnt(0)
	s_barrier
	s_cbranch_vccnz .LBB0_1584
	s_cmp_lt_u32 s68, 4
	s_cbranch_scc1 .Lprio_l1
	s_setprio 1
.Lprio_l1:
	s_load_dwordx2 s[12:13], s[8:9], 0xc0
	s_movk_i32 s42, 0xe000
	s_mov_b32 s15, 0
	v_mov_b32_e32 v1, 0
	s_mov_b32 s80, 0xf800000
	s_waitcnt lgkmcnt(0)
	s_add_u32 s3, s12, 0x14500000
	s_addc_u32 s31, s13, 0
	s_lshl_b32 s8, s68, 2
	s_lshl_b32 s9, s68, 3
	s_lshl_b32 s35, s68, 4
	s_add_i32 s78, s8, 0
	s_add_i32 s78, s78, 0x24800
	s_and_b32 s64, s35, 48
	s_and_b32 s65, s9, 0x1fffffe0
	s_cmp_lg_u32 0, -1
	s_cselect_b32 s8, 0, 0
	s_add_i32 s66, s74, s8
	s_lshl_b32 s8, s69, 2
	s_add_i32 s67, s66, 0x6000
	s_add_i32 s17, s8, 0
	s_lshl_b32 s8, s68, 12
	s_add_i32 s79, s8, 0
	v_mov_b32_e32 v197, 0x260
	s_movk_i32 s82, 0x1ff
	s_add_i32 s83, 0, 0x15000
	s_mov_b32 s16, 0x3fb8aa3b
	s_add_i32 s84, 0, 0x14800
	s_mov_b64 s[18:19], 0x800
	s_lshl_b32 s20, s9, 1
	s_lshl_b32 s22, s65, 1
	v_mov_b32_e32 v202, s66
	v_mov_b32_e32 v203, s67
	s_mov_b64 s[24:25], 0x2000
	v_mov_b32_e32 v204, s74
	s_mov_b64 s[26:27], 0x4000
	s_mov_b64 s[28:29], 0x6000
	s_mov_b64 s[40:41], 0xa000
	s_mov_b32 s43, -1
	s_mov_b32 s85, 0x41000000
	s_mov_b64 s[44:45], 0x1e500000
	v_mov_b32_e32 v205, 0xff800000
	s_mov_b32 s86, s76
	s_branch .LBB0_1405

; __device__ __forceinline__ int mk_tid(int wv) { return (wv << 6) | lane_now(); }
; __device__ __forceinline__ unsigned xb_ld(unsigned* p)              { return __hip_atomic_load(p, __ATOMIC_RELAXED, __HIP_MEMORY_SCOPE_AGENT); }
; __device__ __forceinline__ void xcd_barrier_complete(unsigned* bar, unsigned x, unsigned& nloc, unsigned& nx) {
;     const unsigned G = gridDim.x * gridDim.y * gridDim.z;
;     unsigned sum, cnt, mine, sp = 0u;
;     for (;;) {
;         sum = 0u; cnt = 0u; mine = 0u;
; #pragma unroll
;         for (unsigned j = 0; j < 16; ++j) { const unsigned c = xb_ld(&bar[XB_XCNT(j)]); sum += c; cnt += (c > 0u) ? 1u : 0u; mine = (j == x) ? c : mine; }
;         if (sum == G) break;
; __device__ __forceinline__ void xcd_barrier(const XcdBarrier& b, const int wv) {
;     asm volatile("s_waitcnt vmcnt(0)" ::: "memory");
;     __syncthreads();
;     if (mk_tid(wv) == 0) {
;         unsigned* bar = b.bar;
;         __builtin_amdgcn_s_waitcnt(0);
;         unsigned nloc = b.st[0], nx = b.st[1];
;         if (nloc == 0u) { xcd_barrier_complete(bar, b.x, nloc, nx); b.st[0] = nloc; b.st[1] = nx; }
.LBB0_1584:
	s_setprio 0
	s_mov_b64 s[10:11], s[0:1]
	s_getreg_b32 s3, hwreg(HW_REG_XCC_ID, 0, 4)
	s_waitcnt vmcnt(0)
	s_barrier
	v_mbcnt_lo_u32_b32 v0, -1, 0
	v_mbcnt_hi_u32_b32 v0, -1, v0
	s_nop 0
	v_or_b32_e32 v0, s69, v0
	v_cmp_eq_u32_e32 vcc, 0, v0
	s_and_saveexec_b64 s[8:9], vcc
	s_cbranch_execz .LBB0_1636
	s_add_i32 s12, 0, 0x24840
	v_mov_b32_e32 v0, s12
	s_load_dwordx2 s[10:11], s[10:11], 0xc0
	s_waitcnt vmcnt(0) expcnt(0) lgkmcnt(0)
	ds_read_b32 v2, v0
	s_add_i32 s12, 0, 0x24844
	v_mov_b32_e32 v0, s12
	ds_read_b32 v0, v0
	s_and_b32 s3, s3, 15
	s_waitcnt lgkmcnt(1)
	v_cmp_ne_u32_e32 vcc, 0, v2
	s_cbranch_vccnz .LBB0_1600
	s_add_u32 s12, s10, 0x4200
	s_addc_u32 s13, s11, 0
	s_add_u32 s14, s10, 0x4400
	s_addc_u32 s15, s11, 0
	s_add_u32 s16, s10, 0x4500
	s_addc_u32 s17, s11, 0
	s_add_u32 s18, s10, 0x4600
	s_addc_u32 s19, s11, 0
	s_add_u32 s20, s10, 0x4700
	s_addc_u32 s21, s11, 0
	s_add_u32 s22, s10, 0x4800
	s_addc_u32 s23, s11, 0
	s_add_u32 s24, s10, 0x4900
	s_addc_u32 s25, s11, 0
	s_add_u32 s26, s10, 0x4a00
	s_addc_u32 s27, s11, 0
	s_add_u32 s28, s10, 0x4b00
	s_addc_u32 s29, s11, 0
	s_add_u32 s40, s10, 0x4c00
	s_addc_u32 s41, s11, 0
	s_add_u32 s42, s10, 0x4d00
	s_addc_u32 s43, s11, 0
	s_add_u32 s44, s10, 0x4e00
	s_addc_u32 s45, s11, 0
	s_add_u32 s46, s10, 0x4f00
	s_addc_u32 s47, s11, 0
	s_add_u32 s48, s10, 0x5000
	s_addc_u32 s49, s11, 0
	s_add_u32 s50, s10, 0x5100
	s_addc_u32 s51, s11, 0
	s_add_u32 s52, s10, 0x5200
	s_addc_u32 s53, s11, 0
	s_mul_i32 s31, s37, s33
	s_add_u32 s54, s10, 0x5300
	s_mul_i32 s31, s31, s36
	s_addc_u32 s55, s11, 0
	s_mov_b32 s35, 1
	v_mov_b32_e32 v16, 0
	s_branch .LBB0_1588
